# MA Fourier-path x piece loads of a row issued at the row start (own address arithmetic) so they overlap the first P/Q load
# baseline (speedup 1.0000x reference)
; #define GAS __attribute__((address_space(1)))
; __device__ __forceinline__ void phase_ma(const Params& p, Frame& F, int l, const bool fd, const float* xin32) {
;     ...
;                 const bf16* P = PQ + ((size_t)(b * 4096 + rr)) * 2048;
; #pragma unroll
;                 for (int j = 0; j < 4; ++j) { const int cc = 256 * j + 4 * F.lane; f32x4 y;
;                     if (special) y = *(const f32x4*)(y4096 + b * 1024 + cc); else { const v2u pw = *(const GAS v2u*)(P + cc), qw = *(const GAS v2u*)(P + 1024 + cc);
;                         y.x = bf_lo(pw.x) + sg * bf_lo(qw.x); y.y = bf_hi(pw.x) + sg * bf_hi(qw.x); y.z = bf_lo(pw.y) + sg * bf_lo(qw.y); y.w = bf_hi(pw.y) + sg * bf_hi(qw.y); }
;                     f32x4 xo; if (xin32) xo = *(const GAS f32x4*)(xin32 + (size_t)row * D + cc); else { const v2u xw = *(const GAS v2u*)(xb + (size_t)row * D + cc); xo = (f32x4){bf_lo(xw.x), bf_hi(xw.x), bf_lo(xw.y), bf_hi(xw.y)}; }
.LBB0_632:
	s_xor_b64 s[14:15], s[8:9], -1
	s_add_i32 s8, s18, s34
	s_ashr_i32 s9, s8, 31
	s_lshl_b64 s[8:9], s[8:9], 12
	s_add_u32 s8, s27, s8
	s_addc_u32 s9, s28, s9
	s_mov_b64 s[16:17], -1
	s_and_b64 vcc, exec, s[14:15]
	v_lshl_add_u64 v[68:69], v[66:67], 1, s[8:9]
	v_mov_b32_e32 v192, s2
	v_mov_b32_e32 v193, 0
	s_cmp_lg_u64 s[36:37], 0
	s_cbranch_scc0 .Lmy_pfx_xb_0
	v_lshlrev_b32_e32 v192, 12, v192
	v_lshl_add_u64 v[190:191], v[66:67], 2, v[64:65]
	v_lshl_add_u64 v[190:191], v[192:193], 0, v[190:191]
	global_load_dwordx4 v[194:197], v[190:191], off
	global_load_dwordx4 v[198:201], v[190:191], off offset:1024
	global_load_dwordx4 v[202:205], v[190:191], off offset:2048
	global_load_dwordx4 v[206:209], v[190:191], off offset:3072
	s_branch .Lmy_pfx_done_0
.Lmy_pfx_xb_0:
	v_lshlrev_b32_e32 v192, 11, v192
	v_lshl_add_u64 v[190:191], v[66:67], 1, s[6:7]
	v_lshl_add_u64 v[190:191], v[192:193], 0, v[190:191]
	global_load_dwordx2 v[194:195], v[190:191], off
	global_load_dwordx2 v[198:199], v[190:191], off offset:512
	global_load_dwordx2 v[202:203], v[190:191], off offset:1024
	global_load_dwordx2 v[206:207], v[190:191], off offset:1536
.Lmy_pfx_done_0:
	s_cbranch_vccz .LBB0_634
	s_waitcnt lgkmcnt(0)
	global_load_dwordx2 v[34:35], v[68:69], off
	global_load_dwordx2 v[36:37], v[68:69], off offset:2048
	s_mov_b64 s[16:17], 0
	s_waitcnt vmcnt(0)
	v_lshlrev_b32_e32 v32, 16, v34
	v_and_b32_e32 v33, 0xffff0000, v34
	s_waitcnt vmcnt(0)
	v_lshlrev_b32_e32 v38, 16, v36
	v_and_b32_e32 v39, 0xffff0000, v36
	v_lshlrev_b32_e32 v34, 16, v35
	v_and_b32_e32 v35, 0xffff0000, v35
	v_lshlrev_b32_e32 v36, 16, v37
	v_and_b32_e32 v37, 0xffff0000, v37
	v_pk_fma_f32 v[32:33], s[12:13], v[38:39], v[32:33] op_sel_hi:[0,1,1]
	v_pk_fma_f32 v[34:35], s[12:13], v[36:37], v[34:35] op_sel_hi:[0,1,1]

; #define GAS __attribute__((address_space(1)))
; __device__ __forceinline__ void phase_ma(const Params& p, Frame& F, int l, const bool fd, const float* xin32) {
;     ...
;                     f32x4 xo; if (xin32) xo = *(const GAS f32x4*)(xin32 + (size_t)row * D + cc); else { const v2u xw = *(const GAS v2u*)(xb + (size_t)row * D + cc); xo = (f32x4){bf_lo(xw.x), bf_hi(xw.x), bf_lo(xw.y), bf_hi(xw.y)}; }
.LBB0_636:
	s_ashr_i32 s3, s2, 31
	s_lshl_b64 s[8:9], s[2:3], 11
	s_add_u32 s16, s6, s8
	s_addc_u32 s17, s7, s9
	s_lshl_b64 s[2:3], s[2:3], 12
	v_lshl_add_u64 v[36:37], v[64:65], 0, s[2:3]
	v_lshl_add_u64 v[70:71], v[66:67], 2, v[36:37]
	s_and_saveexec_b64 s[2:3], s[36:37]
	s_xor_b64 s[2:3], exec, s[2:3]
	s_cbranch_execz .LBB0_638
	s_waitcnt vmcnt(0)
	v_mov_b32_e32 v36, v194
	v_mov_b32_e32 v37, v195
	v_mov_b32_e32 v38, v196
	v_mov_b32_e32 v39, v197

; #define GAS __attribute__((address_space(1)))
; __device__ __forceinline__ void phase_ma(const Params& p, Frame& F, int l, const bool fd, const float* xin32) {
;     ...
;                 const bf16* P = PQ + ((size_t)(b * 4096 + rr)) * 2048;
; #pragma unroll
;                 for (int j = 0; j < 4; ++j) { const int cc = 256 * j + 4 * F.lane; f32x4 y;
;                     if (special) y = *(const f32x4*)(y4096 + b * 1024 + cc); else { const v2u pw = *(const GAS v2u*)(P + cc), qw = *(const GAS v2u*)(P + 1024 + cc);
;                         y.x = bf_lo(pw.x) + sg * bf_lo(qw.x); y.y = bf_hi(pw.x) + sg * bf_hi(qw.x); y.z = bf_lo(pw.y) + sg * bf_lo(qw.y); y.w = bf_hi(pw.y) + sg * bf_hi(qw.y); }
;                     f32x4 xo; if (xin32) xo = *(const GAS f32x4*)(xin32 + (size_t)row * D + cc); else { const v2u xw = *(const GAS v2u*)(xb + (size_t)row * D + cc); xo = (f32x4){bf_lo(xw.x), bf_hi(xw.x), bf_lo(xw.y), bf_hi(xw.y)}; }
.LBB0_689:
	s_add_i32 s12, s20, s34
	s_ashr_i32 s13, s12, 31
	s_lshl_b64 s[12:13], s[12:13], 12
	s_add_u32 s12, s27, s12
	s_addc_u32 s13, s28, s13
	s_mov_b64 s[2:3], -1
	s_and_b64 vcc, exec, s[18:19]
	v_lshl_add_u64 v[72:73], v[66:67], 1, s[12:13]
	v_mov_b32_e32 v192, s16
	v_mov_b32_e32 v193, 0
	s_cmp_lg_u64 s[36:37], 0
	s_cbranch_scc0 .Lmy_pfx_xb_1
	v_lshlrev_b32_e32 v192, 12, v192
	v_lshl_add_u64 v[190:191], v[66:67], 2, v[64:65]
	v_lshl_add_u64 v[190:191], v[192:193], 0, v[190:191]
	global_load_dwordx4 v[194:197], v[190:191], off
	global_load_dwordx4 v[198:201], v[190:191], off offset:1024
	global_load_dwordx4 v[202:205], v[190:191], off offset:2048
	global_load_dwordx4 v[206:209], v[190:191], off offset:3072
	s_branch .Lmy_pfx_done_1

; #define GAS __attribute__((address_space(1)))
; __device__ __forceinline__ void phase_ma(const Params& p, Frame& F, int l, const bool fd, const float* xin32) {
;     ...
;                     if (special) y = *(const f32x4*)(y4096 + b * 1024 + cc); else { const v2u pw = *(const GAS v2u*)(P + cc), qw = *(const GAS v2u*)(P + 1024 + cc);
;                         y.x = bf_lo(pw.x) + sg * bf_lo(qw.x); y.y = bf_hi(pw.x) + sg * bf_hi(qw.x); y.z = bf_lo(pw.y) + sg * bf_lo(qw.y); y.w = bf_hi(pw.y) + sg * bf_hi(qw.y); }
.Lmy_pfx_done_1:
	s_cbranch_vccnz .LBB0_691
	s_waitcnt lgkmcnt(0)
	global_load_dwordx2 v[34:35], v[72:73], off
	global_load_dwordx2 v[36:37], v[72:73], off offset:2048
	s_mov_b64 s[2:3], 0
	s_waitcnt vmcnt(0)
	v_lshlrev_b32_e32 v32, 16, v34
	v_and_b32_e32 v33, 0xffff0000, v34
	s_waitcnt vmcnt(0)
	v_lshlrev_b32_e32 v38, 16, v36
	v_and_b32_e32 v39, 0xffff0000, v36
	v_lshlrev_b32_e32 v34, 16, v35
	v_and_b32_e32 v35, 0xffff0000, v35
	v_lshlrev_b32_e32 v36, 16, v37
	v_and_b32_e32 v37, 0xffff0000, v37
	v_pk_fma_f32 v[32:33], s[14:15], v[38:39], v[32:33] op_sel_hi:[0,1,1]
	v_pk_fma_f32 v[34:35], s[14:15], v[36:37], v[34:35] op_sel_hi:[0,1,1]

; #define GAS __attribute__((address_space(1)))
; __device__ __forceinline__ void phase_ma(const Params& p, Frame& F, int l, const bool fd, const float* xin32) {
;     ...
;                     f32x4 xo; if (xin32) xo = *(const GAS f32x4*)(xin32 + (size_t)row * D + cc); else { const v2u xw = *(const GAS v2u*)(xb + (size_t)row * D + cc); xo = (f32x4){bf_lo(xw.x), bf_hi(xw.x), bf_lo(xw.y), bf_hi(xw.y)}; }
.LBB0_693:
	s_ashr_i32 s17, s16, 31
	s_lshl_b64 s[12:13], s[16:17], 11
	s_add_u32 s20, s6, s12
	s_addc_u32 s21, s7, s13
	s_lshl_b64 s[2:3], s[16:17], 12
	v_lshl_add_u64 v[36:37], v[64:65], 0, s[2:3]
	v_lshl_add_u64 v[74:75], v[66:67], 2, v[36:37]
	s_and_saveexec_b64 s[2:3], s[36:37]
	s_xor_b64 s[2:3], exec, s[2:3]
	s_cbranch_execz .LBB0_695
	s_waitcnt vmcnt(0)
	v_mov_b32_e32 v36, v194
	v_mov_b32_e32 v37, v195
	v_mov_b32_e32 v38, v196
	v_mov_b32_e32 v39, v197

; #define GAS __attribute__((address_space(1)))
; __device__ __forceinline__ void phase_ma(const Params& p, Frame& F, int l, const bool fd, const float* xin32) {
;     ...
;         for (int r = 0; r < 4; ++r) { const int row = b * S + s0 + r * rstep; float ss = 0.f;
;             if (fd) { const int k = s0 + r * rstep, m = k & 63, qd = k >> 6; int rr; float sg = 1.0f; bool special = false;
;                 if (m >= 1 && m <= 31) { rr = m * 128 + qd; }
;                 else if (m >= 33) { const int kp = S - k; rr = (kp & 63) * 128 + (kp >> 6); sg = -1.0f; }
;                 else if (m == 0) { if (qd <= 63) rr = qd; else if (qd == 64) { rr = 0; special = true; } else { rr = 128 - qd; sg = -1.0f; } }
;                 else { if (qd <= 63) rr = 64 + qd; else { rr = 64 + (127 - qd); sg = -1.0f; } }
;                 const bf16* P = PQ + ((size_t)(b * 4096 + rr)) * 2048;
; #pragma unroll
;                 for (int j = 0; j < 4; ++j) { const int cc = 256 * j + 4 * F.lane; f32x4 y;
;                     if (special) y = *(const f32x4*)(y4096 + b * 1024 + cc); else { const v2u pw = *(const GAS v2u*)(P + cc), qw = *(const GAS v2u*)(P + 1024 + cc);
;                         y.x = bf_lo(pw.x) + sg * bf_lo(qw.x); y.y = bf_hi(pw.x) + sg * bf_hi(qw.x); y.z = bf_lo(pw.y) + sg * bf_lo(qw.y); y.w = bf_hi(pw.y) + sg * bf_hi(qw.y); }
;                     f32x4 xo; if (xin32) xo = *(const GAS f32x4*)(xin32 + (size_t)row * D + cc); else { const v2u xw = *(const GAS v2u*)(xb + (size_t)row * D + cc); xo = (f32x4){bf_lo(xw.x), bf_hi(xw.x), bf_lo(xw.y), bf_hi(xw.y)}; }
.LBB0_746:
	s_add_i32 s14, s22, s34
	s_ashr_i32 s15, s14, 31
	s_lshl_b64 s[14:15], s[14:15], 12
	s_add_u32 s14, s27, s14
	s_addc_u32 s15, s28, s15
	s_mov_b64 s[2:3], -1
	s_and_b64 vcc, exec, s[20:21]
	v_lshl_add_u64 v[80:81], v[66:67], 1, s[14:15]
	v_mov_b32_e32 v192, s18
	v_mov_b32_e32 v193, 0
	s_cmp_lg_u64 s[36:37], 0
	s_cbranch_scc0 .Lmy_pfx_xb_2
	v_lshlrev_b32_e32 v192, 12, v192
	v_lshl_add_u64 v[190:191], v[66:67], 2, v[64:65]
	v_lshl_add_u64 v[190:191], v[192:193], 0, v[190:191]
	global_load_dwordx4 v[194:197], v[190:191], off
	global_load_dwordx4 v[198:201], v[190:191], off offset:1024
	global_load_dwordx4 v[202:205], v[190:191], off offset:2048
	global_load_dwordx4 v[206:209], v[190:191], off offset:3072
	s_branch .Lmy_pfx_done_2

; #define GAS __attribute__((address_space(1)))
; __device__ __forceinline__ void phase_ma(const Params& p, Frame& F, int l, const bool fd, const float* xin32) {
;     ...
;                 const bf16* P = PQ + ((size_t)(b * 4096 + rr)) * 2048;
; #pragma unroll
;                 for (int j = 0; j < 4; ++j) { const int cc = 256 * j + 4 * F.lane; f32x4 y;
;                     if (special) y = *(const f32x4*)(y4096 + b * 1024 + cc); else { const v2u pw = *(const GAS v2u*)(P + cc), qw = *(const GAS v2u*)(P + 1024 + cc);
;                         y.x = bf_lo(pw.x) + sg * bf_lo(qw.x); y.y = bf_hi(pw.x) + sg * bf_hi(qw.x); y.z = bf_lo(pw.y) + sg * bf_lo(qw.y); y.w = bf_hi(pw.y) + sg * bf_hi(qw.y); }
.Lmy_pfx_done_2:
	s_cbranch_vccnz .LBB0_748
	s_waitcnt lgkmcnt(0)
	global_load_dwordx2 v[34:35], v[80:81], off
	global_load_dwordx2 v[36:37], v[80:81], off offset:2048
	s_mov_b64 s[2:3], 0
	s_waitcnt vmcnt(0)
	v_lshlrev_b32_e32 v32, 16, v34
	v_and_b32_e32 v33, 0xffff0000, v34
	s_waitcnt vmcnt(0)
	v_lshlrev_b32_e32 v38, 16, v36
	v_and_b32_e32 v39, 0xffff0000, v36
	v_lshlrev_b32_e32 v34, 16, v35
	v_and_b32_e32 v35, 0xffff0000, v35
	v_lshlrev_b32_e32 v36, 16, v37
	v_and_b32_e32 v37, 0xffff0000, v37
	v_pk_fma_f32 v[32:33], s[16:17], v[38:39], v[32:33] op_sel_hi:[0,1,1]
	v_pk_fma_f32 v[34:35], s[16:17], v[36:37], v[34:35] op_sel_hi:[0,1,1]

; #define GAS __attribute__((address_space(1)))
; __device__ __forceinline__ unsigned pk2(float lo, float hi) { const f32x2_t v = {lo, hi}; return __builtin_bit_cast(unsigned, __builtin_convertvector(v, bf16x2_t)); }
; __device__ __forceinline__ void phase_ma(const Params& p, Frame& F, int l, const bool fd, const float* xin32) {
;     ...
;                     f32x4 xo; if (xin32) xo = *(const GAS f32x4*)(xin32 + (size_t)row * D + cc); else { const v2u xw = *(const GAS v2u*)(xb + (size_t)row * D + cc); xo = (f32x4){bf_lo(xw.x), bf_hi(xw.x), bf_lo(xw.y), bf_hi(xw.y)}; }
;                     const f32x4 xn = xo + G1[j] * y; v2u ow; ow.x = pk2(xn.x, xn.y); ow.y = pk2(xn.z, xn.w); *(GAS v2u*)(xb + (size_t)row * D + cc) = ow;
.LBB0_750:
	s_ashr_i32 s19, s18, 31
	s_lshl_b64 s[14:15], s[18:19], 11
	s_add_u32 s22, s6, s14
	s_addc_u32 s23, s7, s15
	s_lshl_b64 s[2:3], s[18:19], 12
	v_lshl_add_u64 v[36:37], v[64:65], 0, s[2:3]
	v_lshl_add_u64 v[82:83], v[66:67], 2, v[36:37]
	s_and_saveexec_b64 s[2:3], s[36:37]
	s_xor_b64 s[2:3], exec, s[2:3]
	s_cbranch_execz .LBB0_752
	s_waitcnt vmcnt(0)
	v_mov_b32_e32 v36, v194
	v_mov_b32_e32 v37, v195
	v_mov_b32_e32 v38, v196
	v_mov_b32_e32 v39, v197

; #define GAS __attribute__((address_space(1)))
; __device__ __forceinline__ void phase_ma(const Params& p, Frame& F, int l, const bool fd, const float* xin32) {
;     ...
;         for (int r = 0; r < 4; ++r) { const int row = b * S + s0 + r * rstep; float ss = 0.f;
;             if (fd) { const int k = s0 + r * rstep, m = k & 63, qd = k >> 6; int rr; float sg = 1.0f; bool special = false;
;                 if (m >= 1 && m <= 31) { rr = m * 128 + qd; }
;                 else if (m >= 33) { const int kp = S - k; rr = (kp & 63) * 128 + (kp >> 6); sg = -1.0f; }
;                 else if (m == 0) { if (qd <= 63) rr = qd; else if (qd == 64) { rr = 0; special = true; } else { rr = 128 - qd; sg = -1.0f; } }
;                 else { if (qd <= 63) rr = 64 + qd; else { rr = 64 + (127 - qd); sg = -1.0f; } }
;                 const bf16* P = PQ + ((size_t)(b * 4096 + rr)) * 2048;
; #pragma unroll
;                 for (int j = 0; j < 4; ++j) { const int cc = 256 * j + 4 * F.lane; f32x4 y;
;                     if (special) y = *(const f32x4*)(y4096 + b * 1024 + cc); else { const v2u pw = *(const GAS v2u*)(P + cc), qw = *(const GAS v2u*)(P + 1024 + cc);
;                         y.x = bf_lo(pw.x) + sg * bf_lo(qw.x); y.y = bf_hi(pw.x) + sg * bf_hi(qw.x); y.z = bf_lo(pw.y) + sg * bf_lo(qw.y); y.w = bf_hi(pw.y) + sg * bf_hi(qw.y); }
;                     f32x4 xo; if (xin32) xo = *(const GAS f32x4*)(xin32 + (size_t)row * D + cc); else { const v2u xw = *(const GAS v2u*)(xb + (size_t)row * D + cc); xo = (f32x4){bf_lo(xw.x), bf_hi(xw.x), bf_lo(xw.y), bf_hi(xw.y)}; }
.LBB0_803:
	s_add_i32 s16, s24, s34
	s_ashr_i32 s17, s16, 31
	s_lshl_b64 s[16:17], s[16:17], 12
	s_add_u32 s16, s27, s16
	s_addc_u32 s17, s28, s17
	s_mov_b64 s[2:3], -1
	s_and_b64 vcc, exec, s[22:23]
	v_lshl_add_u64 v[88:89], v[66:67], 1, s[16:17]
	v_mov_b32_e32 v192, s20
	v_mov_b32_e32 v193, 0
	s_cmp_lg_u64 s[36:37], 0
	s_cbranch_scc0 .Lmy_pfx_xb_3
	v_lshlrev_b32_e32 v192, 12, v192
	v_lshl_add_u64 v[190:191], v[66:67], 2, v[64:65]
	v_lshl_add_u64 v[190:191], v[192:193], 0, v[190:191]
	global_load_dwordx4 v[194:197], v[190:191], off
	global_load_dwordx4 v[198:201], v[190:191], off offset:1024
	global_load_dwordx4 v[202:205], v[190:191], off offset:2048
	global_load_dwordx4 v[206:209], v[190:191], off offset:3072
	s_branch .Lmy_pfx_done_3

; #define GAS __attribute__((address_space(1)))
; __device__ __forceinline__ void phase_ma(const Params& p, Frame& F, int l, const bool fd, const float* xin32) {
;     ...
;                 const bf16* P = PQ + ((size_t)(b * 4096 + rr)) * 2048;
; #pragma unroll
;                 for (int j = 0; j < 4; ++j) { const int cc = 256 * j + 4 * F.lane; f32x4 y;
;                     if (special) y = *(const f32x4*)(y4096 + b * 1024 + cc); else { const v2u pw = *(const GAS v2u*)(P + cc), qw = *(const GAS v2u*)(P + 1024 + cc);
;                         y.x = bf_lo(pw.x) + sg * bf_lo(qw.x); y.y = bf_hi(pw.x) + sg * bf_hi(qw.x); y.z = bf_lo(pw.y) + sg * bf_lo(qw.y); y.w = bf_hi(pw.y) + sg * bf_hi(qw.y); }
.Lmy_pfx_done_3:
	s_cbranch_vccnz .LBB0_805
	s_waitcnt lgkmcnt(0)
	global_load_dwordx2 v[34:35], v[88:89], off
	global_load_dwordx2 v[36:37], v[88:89], off offset:2048
	s_mov_b64 s[2:3], 0
	s_waitcnt vmcnt(0)
	v_lshlrev_b32_e32 v32, 16, v34
	v_and_b32_e32 v33, 0xffff0000, v34
	s_waitcnt vmcnt(0)
	v_lshlrev_b32_e32 v38, 16, v36
	v_and_b32_e32 v39, 0xffff0000, v36
	v_lshlrev_b32_e32 v34, 16, v35
	v_and_b32_e32 v35, 0xffff0000, v35
	v_lshlrev_b32_e32 v36, 16, v37
	v_and_b32_e32 v37, 0xffff0000, v37
	v_pk_fma_f32 v[32:33], s[18:19], v[38:39], v[32:33] op_sel_hi:[0,1,1]
	v_pk_fma_f32 v[34:35], s[18:19], v[36:37], v[34:35] op_sel_hi:[0,1,1]

; #define GAS __attribute__((address_space(1)))
; __device__ __forceinline__ unsigned pk2(float lo, float hi) { const f32x2_t v = {lo, hi}; return __builtin_bit_cast(unsigned, __builtin_convertvector(v, bf16x2_t)); }
; __device__ __forceinline__ void phase_ma(const Params& p, Frame& F, int l, const bool fd, const float* xin32) {
;     ...
;                     f32x4 xo; if (xin32) xo = *(const GAS f32x4*)(xin32 + (size_t)row * D + cc); else { const v2u xw = *(const GAS v2u*)(xb + (size_t)row * D + cc); xo = (f32x4){bf_lo(xw.x), bf_hi(xw.x), bf_lo(xw.y), bf_hi(xw.y)}; }
;                     const f32x4 xn = xo + G1[j] * y; v2u ow; ow.x = pk2(xn.x, xn.y); ow.y = pk2(xn.z, xn.w); *(GAS v2u*)(xb + (size_t)row * D + cc) = ow;
.LBB0_807:
	s_ashr_i32 s21, s20, 31
	s_lshl_b64 s[16:17], s[20:21], 11
	s_add_u32 s24, s6, s16
	s_addc_u32 s25, s7, s17
	s_lshl_b64 s[2:3], s[20:21], 12
	v_lshl_add_u64 v[36:37], v[64:65], 0, s[2:3]
	v_lshl_add_u64 v[90:91], v[66:67], 2, v[36:37]
	s_and_saveexec_b64 s[2:3], s[36:37]
	s_xor_b64 s[2:3], exec, s[2:3]
	s_cbranch_execz .LBB0_809
	s_waitcnt vmcnt(0)
	v_mov_b32_e32 v36, v194
	v_mov_b32_e32 v37, v195
	v_mov_b32_e32 v38, v196
	v_mov_b32_e32 v39, v197
